# gla_finalize: streaming (nt) hint on its single-use full-line loads, on top of the P1 gate-store hint
# baseline (speedup 1.0000x reference)
; __device__ __forceinline__ float ss_total(const float* ss, int row) { const f32x4* sp = (const f32x4*)(ss + (size_t)row * 16); const f32x4 a = sp[0], b = sp[1], c = sp[2], d = sp[3];
;     return (((a[0] + a[1]) + (a[2] + a[3])) + ((b[0] + b[1]) + (b[2] + b[3]))) + (((c[0] + c[1]) + (c[2] + c[3])) + ((d[0] + d[1]) + (d[2] + d[3]))); }
; __device__ __forceinline__ void gla_finalize(const Ctx& P, int l) {
;     ...
;     for (int it0 = gt; it0 < MP * 128; it0 += 4 * NT) {
;         u32x4 ovw[4], gvw[4]; float rs[4];
; #pragma unroll
;         for (int u = 0; u < 4; ++u) { const int it = it0 + u * NT; if (it < MP * 128) { const int row = it >> 7, c8 = (it & 127) * 8, h = c8 >> 8;
;             ovw[u] = *(const u32x4*)(OG + (size_t)row * D + c8); gvw[u] = *(const u32x4*)(Z + (size_t)row * NZ + ZC_GOUT + c8);
;             rs[u] = rsqrtf(ss_total(GSS + (size_t)h * 16, row * 4) * (1.f / 256.f) + EPS); } }
.LBB0_677:
	v_lshrrev_b32_e32 v0, 2, v50
	v_readlane_b32 s10, v249, 54
	v_and_b32_e32 v30, 0xc0, v0
	v_mov_b32_e32 v31, v1
	v_readlane_b32 s11, v249, 55
	v_readlane_b32 s12, v251, 5
	v_readlane_b32 s14, v251, 7
	v_lshl_add_u64 v[38:39], s[10:11], 0, v[30:31]
	v_ashrrev_i32_e32 v30, 7, v41
	v_lshlrev_b32_e32 v32, 2, v30
	v_ashrrev_i32_e32 v33, 31, v32
	v_lshlrev_b64 v[32:33], 6, v[32:33]
	v_lshl_add_u64 v[32:33], v[38:39], 0, v[32:33]
	global_load_dwordx4 v[52:55], v[32:33], off nt
	global_load_dwordx4 v[56:59], v[32:33], off offset:32 nt
	global_load_dwordx4 v[60:63], v[32:33], off offset:16 nt
	global_load_dwordx4 v[64:67], v[32:33], off offset:48 nt
	v_readlane_b32 s15, v251, 8
	v_and_b32_e32 v40, 0x3f8, v50
	v_lshlrev_b32_e32 v0, 1, v40
	v_mov_b64_e32 v[32:33], s[14:15]
	v_mad_i64_i32 v[32:33], s[10:11], v30, s67, v[32:33]
	v_readlane_b32 s10, v249, 37
	v_ashrrev_i32_e32 v31, 31, v30
	v_readlane_b32 s11, v249, 38
	v_lshlrev_b64 v[30:31], 11, v[30:31]
	v_lshl_add_u64 v[32:33], v[32:33], 0, v[0:1]
	v_lshl_add_u64 v[42:43], s[10:11], 0, v[0:1]
	s_mov_b32 s10, 0xfc82000
	v_lshl_add_u64 v[46:47], v[42:43], 0, v[30:31]
	v_add_co_u32_e32 v30, vcc, s10, v32
	v_add_u32_e32 v51, s79, v41
	s_nop 0
	v_addc_co_u32_e32 v31, vcc, 0, v33, vcc
	global_load_dwordx4 v[34:37], v[46:47], off nt
	s_nop 0
	global_load_dwordx4 v[30:33], v[30:31], off nt
	s_mov_b32 s10, 0x204000
	v_cmp_gt_i32_e64 s[42:43], s10, v51
	v_readlane_b32 s13, v251, 6
	s_waitcnt vmcnt(0)
	v_mov_b32_e32 v44, v52
	v_mov_b32_e32 v45, v56
	v_mov_b32_e32 v56, v53
	v_mov_b32_e32 v48, v54
	v_mov_b32_e32 v49, v58
	v_mov_b32_e32 v58, v55
	v_mov_b32_e32 v52, v60
	v_mov_b32_e32 v53, v64
	v_mov_b32_e32 v64, v61
	v_mov_b32_e32 v54, v62
	v_mov_b32_e32 v55, v66
	v_mov_b32_e32 v66, v63
	v_pk_add_f32 v[44:45], v[44:45], v[56:57]
	v_pk_add_f32 v[48:49], v[48:49], v[58:59]
	v_pk_add_f32 v[52:53], v[52:53], v[64:65]
	v_pk_add_f32 v[54:55], v[54:55], v[66:67]
	v_pk_add_f32 v[44:45], v[44:45], v[48:49]
	v_pk_add_f32 v[48:49], v[52:53], v[54:55]
	s_nop 0
	v_pk_add_f32 v[44:45], v[44:45], v[48:49]
	s_nop 0
	v_add_f32_e32 v2, v44, v45
	v_fmamk_f32 v2, v2, 0x3b800000, v190
	v_mul_f32_e32 v44, 0x4b800000, v2
	v_cmp_gt_f32_e32 vcc, s66, v2
	s_nop 1
	v_cndmask_b32_e32 v2, v2, v44, vcc
	v_rsq_f32_e32 v2, v2
	s_nop 0
	v_mul_f32_e32 v44, 0x45800000, v2
	v_cndmask_b32_e32 v2, v2, v44, vcc
	s_and_saveexec_b64 s[10:11], s[42:43]
	s_cbranch_execz .LBB0_679
	v_ashrrev_i32_e32 v6, 7, v51
	v_lshlrev_b32_e32 v8, 2, v6
	v_ashrrev_i32_e32 v9, 31, v8
	v_lshlrev_b64 v[8:9], 6, v[8:9]
	v_lshl_add_u64 v[8:9], v[38:39], 0, v[8:9]
	global_load_dwordx4 v[52:55], v[8:9], off nt
	global_load_dwordx4 v[56:59], v[8:9], off offset:32 nt
	global_load_dwordx4 v[60:63], v[8:9], off offset:16 nt
	global_load_dwordx4 v[64:67], v[8:9], off offset:48 nt
	v_readlane_b32 s12, v251, 5
	v_readlane_b32 s14, v251, 7
	v_readlane_b32 s15, v251, 8
	v_readlane_b32 s13, v251, 6
	v_ashrrev_i32_e32 v7, 31, v6
	v_mov_b64_e32 v[8:9], s[14:15]
	v_mad_i64_i32 v[8:9], s[12:13], v6, s67, v[8:9]
	v_lshl_add_u64 v[8:9], v[8:9], 0, v[0:1]
	v_lshlrev_b64 v[6:7], 11, v[6:7]
	v_add_co_u32_e32 v18, vcc, 0xfc82000, v8
	v_lshl_add_u64 v[6:7], v[42:43], 0, v[6:7]
	s_nop 0
	v_addc_co_u32_e32 v19, vcc, 0, v9, vcc
	global_load_dwordx4 v[6:9], v[6:7], off nt
	s_nop 0
	global_load_dwordx4 v[18:21], v[18:19], off nt
	s_waitcnt vmcnt(5)
	v_mov_b32_e32 v44, v52
	s_waitcnt vmcnt(4)
	v_mov_b32_e32 v45, v56
	v_mov_b32_e32 v56, v53
	v_mov_b32_e32 v48, v54
	v_mov_b32_e32 v49, v58
	v_mov_b32_e32 v58, v55
	s_waitcnt vmcnt(3)
	v_mov_b32_e32 v52, v60
	s_waitcnt vmcnt(2)
	v_mov_b32_e32 v53, v64
	v_mov_b32_e32 v64, v61
	v_mov_b32_e32 v54, v62
	v_mov_b32_e32 v55, v66
	v_mov_b32_e32 v66, v63
	v_pk_add_f32 v[44:45], v[44:45], v[56:57]
	v_pk_add_f32 v[48:49], v[48:49], v[58:59]
	v_pk_add_f32 v[52:53], v[52:53], v[64:65]
	v_pk_add_f32 v[54:55], v[54:55], v[66:67]
	v_pk_add_f32 v[44:45], v[44:45], v[48:49]
	v_pk_add_f32 v[48:49], v[52:53], v[54:55]
	s_nop 0
	v_pk_add_f32 v[44:45], v[44:45], v[48:49]
	s_nop 0
	v_add_f32_e32 v3, v44, v45
	v_fmamk_f32 v3, v3, 0x3b800000, v190
	v_mul_f32_e32 v44, 0x4b800000, v3
	v_cmp_gt_f32_e32 vcc, s66, v3
	s_nop 1
	v_cndmask_b32_e32 v3, v3, v44, vcc
	v_rsq_f32_e32 v3, v3
	s_nop 0
	v_mul_f32_e32 v44, 0x45800000, v3
	v_cndmask_b32_e32 v3, v3, v44, vcc
.LBB0_679:
	s_or_b64 exec, exec, s[10:11]
	v_readlane_b32 s10, v250, 9
	s_nop 1
	v_add_u32_e32 v53, s10, v41
	s_mov_b32 s10, 0x204000
	v_cmp_gt_i32_e64 s[40:41], s10, v53
	s_and_saveexec_b64 s[10:11], s[40:41]
	s_cbranch_execz .LBB0_681
	v_ashrrev_i32_e32 v14, 7, v53
	v_lshlrev_b32_e32 v16, 2, v14
	v_ashrrev_i32_e32 v17, 31, v16
	v_lshlrev_b64 v[16:17], 6, v[16:17]
	v_lshl_add_u64 v[16:17], v[38:39], 0, v[16:17]
	global_load_dwordx4 v[54:57], v[16:17], off nt
	global_load_dwordx4 v[58:61], v[16:17], off offset:32 nt
	global_load_dwordx4 v[62:65], v[16:17], off offset:16 nt
	global_load_dwordx4 v[66:69], v[16:17], off offset:48 nt
	v_readlane_b32 s12, v251, 5
	v_readlane_b32 s14, v251, 7
	v_readlane_b32 s15, v251, 8
	v_readlane_b32 s13, v251, 6
	v_ashrrev_i32_e32 v15, 31, v14
	v_mov_b64_e32 v[16:17], s[14:15]
	v_mad_i64_i32 v[16:17], s[12:13], v14, s67, v[16:17]
	v_lshl_add_u64 v[16:17], v[16:17], 0, v[0:1]
	v_lshlrev_b64 v[14:15], 11, v[14:15]
	v_add_co_u32_e32 v26, vcc, 0xfc82000, v16
	v_lshl_add_u64 v[14:15], v[42:43], 0, v[14:15]
	s_nop 0
	v_addc_co_u32_e32 v27, vcc, 0, v17, vcc
	global_load_dwordx4 v[14:17], v[14:15], off nt
	s_nop 0
	global_load_dwordx4 v[26:29], v[26:27], off nt
	s_waitcnt vmcnt(5)
	v_mov_b32_e32 v44, v54
	s_waitcnt vmcnt(4)
	v_mov_b32_e32 v45, v58
	v_mov_b32_e32 v58, v55
	v_mov_b32_e32 v48, v56
	v_mov_b32_e32 v49, v60
	v_mov_b32_e32 v60, v57
	s_waitcnt vmcnt(3)
	v_mov_b32_e32 v54, v62
	s_waitcnt vmcnt(2)
	v_mov_b32_e32 v55, v66
	v_mov_b32_e32 v66, v63
	v_mov_b32_e32 v56, v64
	v_mov_b32_e32 v57, v68
	v_mov_b32_e32 v68, v65
	v_pk_add_f32 v[44:45], v[44:45], v[58:59]
	v_pk_add_f32 v[48:49], v[48:49], v[60:61]
	v_pk_add_f32 v[54:55], v[54:55], v[66:67]
	v_pk_add_f32 v[56:57], v[56:57], v[68:69]
	v_pk_add_f32 v[44:45], v[44:45], v[48:49]
	v_pk_add_f32 v[48:49], v[54:55], v[56:57]
	s_nop 0
	v_pk_add_f32 v[44:45], v[44:45], v[48:49]
	s_nop 0
	v_add_f32_e32 v4, v44, v45
	v_fmamk_f32 v4, v4, 0x3b800000, v190
	v_mul_f32_e32 v44, 0x4b800000, v4
	v_cmp_gt_f32_e32 vcc, s66, v4
	s_nop 1
	v_cndmask_b32_e32 v4, v4, v44, vcc
	v_rsq_f32_e32 v4, v4
	s_nop 0
	v_mul_f32_e32 v44, 0x45800000, v4
	v_cndmask_b32_e32 v4, v4, v44, vcc
; __device__ __forceinline__ unsigned pk2(float lo, float hi) { f32x2 v = {lo, hi}; bf16x2_t b = __builtin_convertvector(v, bf16x2_t); return __builtin_bit_cast(unsigned, b); }
; __device__ __forceinline__ float silu_(float x) { return x * sigm(x); }
; __device__ __forceinline__ void unpack8(const u32x4 w, float (&f)[8]) { f[0] = bflo(w.x); f[1] = bfhi(w.x); f[2] = bflo(w.y); f[3] = bfhi(w.y); f[4] = bflo(w.z); f[5] = bfhi(w.z); f[6] = bflo(w.w); f[7] = bfhi(w.w); }
; __device__ __forceinline__ void gla_finalize(const Ctx& P, int l) {
;     ...
;         for (int u = 0; u < 4; ++u) { const int it = it0 + u * NT; if (it < MP * 128) { const int row = it >> 7, c8 = (it & 127) * 8, h = c8 >> 8;
;             ovw[u] = *(const u32x4*)(OG + (size_t)row * D + c8); gvw[u] = *(const u32x4*)(Z + (size_t)row * NZ + ZC_GOUT + c8);
;             rs[u] = rsqrtf(ss_total(GSS + (size_t)h * 16, row * 4) * (1.f / 256.f) + EPS); } }
; #pragma unroll
;         for (int u = 0; u < 4; ++u) { const int it = it0 + u * NT; if (it < MP * 128) { const int row = it >> 7, c8 = (it & 127) * 8;
;             float ov[8], gv[8], gn[8]; unpack8(ovw[u], ov); unpack8(gvw[u], gv); load8f(p_gn + c8, gn);
; #pragma unroll
;             for (int i = 0; i < 8; ++i) ov[i] = ov[i] * rs[u] * gn[i] * silu_(gv[i]);
;             u32x4 o; o.x = pk2(ov[0], ov[1]); o.y = pk2(ov[2], ov[3]); o.z = pk2(ov[4], ov[5]); o.w = pk2(ov[6], ov[7]);
;             *(u32x4*)(OG + (size_t)row * D + c8) = o; } }
.LBB0_681:
	s_or_b64 exec, exec, s[10:11]
	s_mul_i32 s10, s62, 0x600
	v_add_u32_e32 v52, s10, v41
	s_mov_b32 s10, 0x204000
	v_cmp_gt_i32_e64 s[38:39], s10, v52
	s_and_saveexec_b64 s[10:11], s[38:39]
	s_cbranch_execz .LBB0_683
	v_ashrrev_i32_e32 v10, 7, v52
	v_lshlrev_b32_e32 v12, 2, v10
	v_ashrrev_i32_e32 v13, 31, v12
	v_lshlrev_b64 v[12:13], 6, v[12:13]
	v_lshl_add_u64 v[12:13], v[38:39], 0, v[12:13]
	global_load_dwordx4 v[54:57], v[12:13], off nt
	global_load_dwordx4 v[58:61], v[12:13], off offset:32 nt
	global_load_dwordx4 v[62:65], v[12:13], off offset:16 nt
	global_load_dwordx4 v[66:69], v[12:13], off offset:48 nt
	v_readlane_b32 s12, v251, 5
	v_readlane_b32 s14, v251, 7
	v_readlane_b32 s15, v251, 8
	v_readlane_b32 s13, v251, 6
	v_ashrrev_i32_e32 v11, 31, v10
	v_mov_b64_e32 v[12:13], s[14:15]
	v_mad_i64_i32 v[12:13], s[12:13], v10, s67, v[12:13]
	v_lshl_add_u64 v[12:13], v[12:13], 0, v[0:1]
	v_lshlrev_b64 v[10:11], 11, v[10:11]
	v_add_co_u32_e32 v22, vcc, 0xfc82000, v12
	v_lshl_add_u64 v[10:11], v[42:43], 0, v[10:11]
	s_nop 0
	v_addc_co_u32_e32 v23, vcc, 0, v13, vcc
	global_load_dwordx4 v[10:13], v[10:11], off nt
	s_nop 0
	global_load_dwordx4 v[22:25], v[22:23], off nt
	s_waitcnt vmcnt(5)
	v_mov_b32_e32 v38, v54
	s_waitcnt vmcnt(4)
	v_mov_b32_e32 v39, v58
	v_mov_b32_e32 v58, v55
	v_mov_b32_e32 v44, v56
	v_mov_b32_e32 v45, v60
	v_mov_b32_e32 v60, v57
	s_waitcnt vmcnt(3)
	v_mov_b32_e32 v48, v62
	s_waitcnt vmcnt(2)
	v_mov_b32_e32 v49, v66
	v_mov_b32_e32 v66, v63
	v_mov_b32_e32 v54, v64
	v_mov_b32_e32 v55, v68
	v_mov_b32_e32 v68, v65
	v_pk_add_f32 v[38:39], v[38:39], v[58:59]
	v_pk_add_f32 v[44:45], v[44:45], v[60:61]
	v_pk_add_f32 v[48:49], v[48:49], v[66:67]
	v_pk_add_f32 v[54:55], v[54:55], v[68:69]
	v_pk_add_f32 v[38:39], v[38:39], v[44:45]
	v_pk_add_f32 v[44:45], v[48:49], v[54:55]
	s_nop 0
	v_pk_add_f32 v[38:39], v[38:39], v[44:45]
	s_nop 0
	v_add_f32_e32 v0, v38, v39
	v_fmamk_f32 v0, v0, 0x3b800000, v190
	v_mul_f32_e32 v5, 0x4b800000, v0
	v_cmp_gt_f32_e32 vcc, s66, v0
	s_nop 1
	v_cndmask_b32_e32 v0, v0, v5, vcc
	v_rsq_f32_e32 v0, v0
	s_nop 0
	v_mul_f32_e32 v5, 0x45800000, v0
	v_cndmask_b32_e32 v5, v0, v5, vcc
.LBB0_683:
	s_or_b64 exec, exec, s[10:11]
	v_lshlrev_b32_e32 v0, 2, v40
	v_lshl_add_u64 v[44:45], s[4:5], 0, v[0:1]
	flat_load_dwordx4 v[54:57], v[44:45] nt
	flat_load_dwordx4 v[38:41], v[44:45] offset:16 nt
	v_lshlrev_b32_e32 v58, 16, v30
	v_mul_f32_e32 v0, 0xbfb8aa3b, v58
	v_exp_f32_e32 v0, v0
	v_and_b32_e32 v59, 0xffff0000, v30
	v_lshlrev_b32_e32 v30, 16, v31
	v_lshlrev_b32_e32 v48, 16, v34
	v_add_f32_e32 v0, 1.0, v0
	v_rcp_f32_e32 v60, v0
	v_mul_f32_e32 v0, 0xbfb8aa3b, v59
	v_exp_f32_e32 v0, v0
	v_and_b32_e32 v49, 0xffff0000, v34
	v_pk_mul_f32 v[48:49], v[2:3], v[48:49] op_sel_hi:[0,1]
	v_and_b32_e32 v31, 0xffff0000, v31
	v_add_f32_e32 v0, 1.0, v0
	v_rcp_f32_e32 v61, v0
	v_mul_f32_e32 v0, 0xbfb8aa3b, v30
	v_exp_f32_e32 v0, v0
	v_lshlrev_b32_e32 v34, 16, v35
	v_and_b32_e32 v35, 0xffff0000, v35
	v_pk_mul_f32 v[34:35], v[2:3], v[34:35] op_sel_hi:[0,1]
	v_add_f32_e32 v0, 1.0, v0
	s_waitcnt vmcnt(0) lgkmcnt(0)
	v_pk_mul_f32 v[48:49], v[54:55], v[48:49]
	v_pk_mul_f32 v[54:55], v[60:61], v[58:59]
	v_pk_mul_f32 v[34:35], v[56:57], v[34:35]
	v_pk_mul_f32 v[48:49], v[54:55], v[48:49]
	v_rcp_f32_e32 v54, v0
	v_mul_f32_e32 v0, 0xbfb8aa3b, v31
	v_exp_f32_e32 v0, v0
	s_nop 0
	v_add_f32_e32 v0, 1.0, v0
	v_rcp_f32_e32 v55, v0
	s_nop 0
	v_pk_mul_f32 v[30:31], v[54:55], v[30:31]
	v_lshlrev_b32_e32 v54, 16, v32
	v_mul_f32_e32 v0, 0xbfb8aa3b, v54
	v_exp_f32_e32 v0, v0
	v_and_b32_e32 v55, 0xffff0000, v32
	v_lshlrev_b32_e32 v32, 16, v33
	v_pk_mul_f32 v[30:31], v[30:31], v[34:35]
	v_add_f32_e32 v0, 1.0, v0
	v_rcp_f32_e32 v56, v0
	v_mul_f32_e32 v0, 0xbfb8aa3b, v55
	v_exp_f32_e32 v0, v0
	v_lshlrev_b32_e32 v34, 16, v36
	v_and_b32_e32 v35, 0xffff0000, v36
	v_pk_mul_f32 v[34:35], v[2:3], v[34:35] op_sel_hi:[0,1]
	v_add_f32_e32 v0, 1.0, v0
	v_rcp_f32_e32 v57, v0
	v_mul_f32_e32 v0, 0xbfb8aa3b, v32
	v_exp_f32_e32 v0, v0
	v_pk_mul_f32 v[34:35], v[34:35], v[38:39]
	v_pk_mul_f32 v[38:39], v[56:57], v[54:55]
	v_and_b32_e32 v33, 0xffff0000, v33
	v_add_f32_e32 v0, 1.0, v0
	v_pk_mul_f32 v[34:35], v[38:39], v[34:35]
	v_rcp_f32_e32 v38, v0
	v_mul_f32_e32 v0, 0xbfb8aa3b, v33
	v_exp_f32_e32 v0, v0
	v_lshlrev_b32_e32 v36, 16, v37
	v_and_b32_e32 v37, 0xffff0000, v37
	v_pk_mul_f32 v[36:37], v[2:3], v[36:37] op_sel_hi:[0,1]
	v_add_f32_e32 v0, 1.0, v0
	v_rcp_f32_e32 v39, v0
	v_pk_mul_f32 v[36:37], v[36:37], v[40:41]
	v_cvt_pk_bf16_f32 v34, v34, v35
	v_pk_mul_f32 v[32:33], v[38:39], v[32:33]
	s_nop 0
	v_pk_mul_f32 v[36:37], v[32:33], v[36:37]
	v_cvt_pk_bf16_f32 v32, v48, v49
	v_cvt_pk_bf16_f32 v33, v30, v31
	v_cvt_pk_bf16_f32 v35, v36, v37
	global_store_dwordx4 v[46:47], v[32:35], off
	s_and_saveexec_b64 s[10:11], s[42:43]
	s_cbranch_execnz .LBB0_686
	s_or_b64 exec, exec, s[10:11]
	s_and_saveexec_b64 s[10:11], s[40:41]
	s_cbranch_execnz .LBB0_687

; __device__ __forceinline__ unsigned pk2(float lo, float hi) { f32x2 v = {lo, hi}; bf16x2_t b = __builtin_convertvector(v, bf16x2_t); return __builtin_bit_cast(unsigned, b); }
; __device__ __forceinline__ float silu_(float x) { return x * sigm(x); }
; __device__ __forceinline__ void unpack8(const u32x4 w, float (&f)[8]) { f[0] = bflo(w.x); f[1] = bfhi(w.x); f[2] = bflo(w.y); f[3] = bfhi(w.y); f[4] = bflo(w.z); f[5] = bfhi(w.z); f[6] = bflo(w.w); f[7] = bfhi(w.w); }
; __device__ __forceinline__ void gla_finalize(const Ctx& P, int l) {
;     ...
;         for (int u = 0; u < 4; ++u) { const int it = it0 + u * NT; if (it < MP * 128) { const int row = it >> 7, c8 = (it & 127) * 8;
;             float ov[8], gv[8], gn[8]; unpack8(ovw[u], ov); unpack8(gvw[u], gv); load8f(p_gn + c8, gn);
; #pragma unroll
;             for (int i = 0; i < 8; ++i) ov[i] = ov[i] * rs[u] * gn[i] * silu_(gv[i]);
;             u32x4 o; o.x = pk2(ov[0], ov[1]); o.y = pk2(ov[2], ov[3]); o.z = pk2(ov[4], ov[5]); o.w = pk2(ov[6], ov[7]);
;             *(u32x4*)(OG + (size_t)row * D + c8) = o; } }
.LBB0_686:
	flat_load_dwordx4 v[30:33], v[44:45] nt
	flat_load_dwordx4 v[34:37], v[44:45] offset:16 nt
	v_lshlrev_b32_e32 v40, 16, v18
	v_mul_f32_e32 v0, 0xbfb8aa3b, v40
	v_exp_f32_e32 v0, v0
	v_and_b32_e32 v41, 0xffff0000, v18
	v_lshlrev_b32_e32 v38, 16, v6
	v_and_b32_e32 v39, 0xffff0000, v6
	v_add_f32_e32 v0, 1.0, v0
	v_rcp_f32_e32 v46, v0
	v_mul_f32_e32 v0, 0xbfb8aa3b, v41
	v_exp_f32_e32 v0, v0
	v_pk_mul_f32 v[38:39], v[2:3], v[38:39] op_sel:[1,0]
	v_add_f32_e32 v0, 1.0, v0
	v_rcp_f32_e32 v47, v0
	s_waitcnt vmcnt(0) lgkmcnt(0)
	v_pk_mul_f32 v[30:31], v[38:39], v[30:31]
	v_pk_mul_f32 v[38:39], v[46:47], v[40:41]
	v_lshlrev_b32_e32 v40, 16, v19
	v_mul_f32_e32 v0, 0xbfb8aa3b, v40
	v_exp_f32_e32 v0, v0
	v_and_b32_e32 v41, 0xffff0000, v19
	v_pk_mul_f32 v[30:31], v[38:39], v[30:31]
	v_lshlrev_b32_e32 v38, 16, v7
	v_add_f32_e32 v0, 1.0, v0
	v_rcp_f32_e32 v46, v0
	v_mul_f32_e32 v0, 0xbfb8aa3b, v41
	v_exp_f32_e32 v0, v0
	v_and_b32_e32 v39, 0xffff0000, v7
	v_pk_mul_f32 v[38:39], v[2:3], v[38:39] op_sel:[1,0]
	v_cvt_pk_bf16_f32 v30, v30, v31
	v_add_f32_e32 v0, 1.0, v0
	v_rcp_f32_e32 v47, v0
	v_pk_mul_f32 v[32:33], v[38:39], v[32:33]
	v_pk_mul_f32 v[38:39], v[46:47], v[40:41]
	v_lshlrev_b32_e32 v40, 16, v20
	v_mul_f32_e32 v0, 0xbfb8aa3b, v40
	v_exp_f32_e32 v0, v0
	v_and_b32_e32 v41, 0xffff0000, v20
	v_pk_mul_f32 v[32:33], v[38:39], v[32:33]
	v_lshlrev_b32_e32 v38, 16, v8
	v_add_f32_e32 v0, 1.0, v0
	v_rcp_f32_e32 v46, v0
	v_mul_f32_e32 v0, 0xbfb8aa3b, v41
	v_exp_f32_e32 v0, v0
	v_and_b32_e32 v39, 0xffff0000, v8
	v_pk_mul_f32 v[38:39], v[2:3], v[38:39] op_sel:[1,0]
	v_cvt_pk_bf16_f32 v31, v32, v33
	v_add_f32_e32 v0, 1.0, v0
	v_rcp_f32_e32 v47, v0
	v_pk_mul_f32 v[34:35], v[38:39], v[34:35]
	v_pk_mul_f32 v[38:39], v[46:47], v[40:41]
	v_lshlrev_b32_e32 v40, 16, v21
	v_mul_f32_e32 v0, 0xbfb8aa3b, v40
	v_exp_f32_e32 v0, v0
	v_and_b32_e32 v41, 0xffff0000, v21
	v_pk_mul_f32 v[34:35], v[38:39], v[34:35]
	v_lshlrev_b32_e32 v38, 16, v9
	v_add_f32_e32 v0, 1.0, v0
	v_rcp_f32_e32 v46, v0
	v_mul_f32_e32 v0, 0xbfb8aa3b, v41
	v_exp_f32_e32 v0, v0
	v_and_b32_e32 v39, 0xffff0000, v9
	v_pk_mul_f32 v[38:39], v[2:3], v[38:39] op_sel:[1,0]
	v_cvt_pk_bf16_f32 v32, v34, v35
	v_add_f32_e32 v0, 1.0, v0
	v_rcp_f32_e32 v47, v0
	v_pk_mul_f32 v[36:37], v[38:39], v[36:37]
	v_pk_mul_f32 v[38:39], v[46:47], v[40:41]
	s_nop 0
	v_pk_mul_f32 v[36:37], v[38:39], v[36:37]
	v_ashrrev_i32_e32 v38, 7, v51
	v_ashrrev_i32_e32 v39, 31, v38
	v_lshlrev_b64 v[34:35], 11, v[38:39]
	v_cvt_pk_bf16_f32 v33, v36, v37
	v_lshl_add_u64 v[34:35], v[42:43], 0, v[34:35]
	global_store_dwordx4 v[34:35], v[30:33], off
	s_or_b64 exec, exec, s[10:11]
	s_and_saveexec_b64 s[10:11], s[40:41]
	s_cbranch_execz .LBB0_685
; __device__ __forceinline__ unsigned pk2(float lo, float hi) { f32x2 v = {lo, hi}; bf16x2_t b = __builtin_convertvector(v, bf16x2_t); return __builtin_bit_cast(unsigned, b); }
; __device__ __forceinline__ float silu_(float x) { return x * sigm(x); }
; __device__ __forceinline__ void unpack8(const u32x4 w, float (&f)[8]) { f[0] = bflo(w.x); f[1] = bfhi(w.x); f[2] = bflo(w.y); f[3] = bfhi(w.y); f[4] = bflo(w.z); f[5] = bfhi(w.z); f[6] = bflo(w.w); f[7] = bfhi(w.w); }
; __device__ __forceinline__ void gla_finalize(const Ctx& P, int l) {
;     ...
;         for (int u = 0; u < 4; ++u) { const int it = it0 + u * NT; if (it < MP * 128) { const int row = it >> 7, c8 = (it & 127) * 8;
;             float ov[8], gv[8], gn[8]; unpack8(ovw[u], ov); unpack8(gvw[u], gv); load8f(p_gn + c8, gn);
; #pragma unroll
;             for (int i = 0; i < 8; ++i) ov[i] = ov[i] * rs[u] * gn[i] * silu_(gv[i]);
;             u32x4 o; o.x = pk2(ov[0], ov[1]); o.y = pk2(ov[2], ov[3]); o.z = pk2(ov[4], ov[5]); o.w = pk2(ov[6], ov[7]);
;             *(u32x4*)(OG + (size_t)row * D + c8) = o; } }
.LBB0_687:
	flat_load_dwordx4 v[30:33], v[44:45] nt
	flat_load_dwordx4 v[34:37], v[44:45] offset:16 nt
	v_lshlrev_b32_e32 v40, 16, v26
	v_mul_f32_e32 v0, 0xbfb8aa3b, v40
	v_exp_f32_e32 v0, v0
	v_and_b32_e32 v41, 0xffff0000, v26
	v_lshlrev_b32_e32 v38, 16, v14
	v_and_b32_e32 v39, 0xffff0000, v14
	v_add_f32_e32 v0, 1.0, v0
	v_rcp_f32_e32 v46, v0
	v_mul_f32_e32 v0, 0xbfb8aa3b, v41
	v_exp_f32_e32 v0, v0
	v_pk_mul_f32 v[38:39], v[4:5], v[38:39] op_sel_hi:[0,1]
	v_add_f32_e32 v0, 1.0, v0
	v_rcp_f32_e32 v47, v0
	s_waitcnt vmcnt(0) lgkmcnt(0)
	v_pk_mul_f32 v[30:31], v[38:39], v[30:31]
	v_pk_mul_f32 v[38:39], v[46:47], v[40:41]
	v_lshlrev_b32_e32 v40, 16, v27
	v_mul_f32_e32 v0, 0xbfb8aa3b, v40
	v_exp_f32_e32 v0, v0
	v_and_b32_e32 v41, 0xffff0000, v27
	v_pk_mul_f32 v[30:31], v[38:39], v[30:31]
	v_lshlrev_b32_e32 v38, 16, v15
	v_add_f32_e32 v0, 1.0, v0
	v_rcp_f32_e32 v46, v0
	v_mul_f32_e32 v0, 0xbfb8aa3b, v41
	v_exp_f32_e32 v0, v0
	v_and_b32_e32 v39, 0xffff0000, v15
	v_pk_mul_f32 v[38:39], v[4:5], v[38:39] op_sel_hi:[0,1]
	v_pk_mul_f32 v[32:33], v[38:39], v[32:33]
	v_add_f32_e32 v0, 1.0, v0
	v_rcp_f32_e32 v47, v0
	v_cvt_pk_bf16_f32 v30, v30, v31
	v_pk_mul_f32 v[38:39], v[46:47], v[40:41]
	v_lshlrev_b32_e32 v40, 16, v28
	v_mul_f32_e32 v0, 0xbfb8aa3b, v40
	v_exp_f32_e32 v0, v0
	v_and_b32_e32 v41, 0xffff0000, v28
	v_pk_mul_f32 v[32:33], v[38:39], v[32:33]
	v_lshlrev_b32_e32 v38, 16, v16
	v_add_f32_e32 v0, 1.0, v0
	v_rcp_f32_e32 v46, v0
	v_mul_f32_e32 v0, 0xbfb8aa3b, v41
	v_exp_f32_e32 v0, v0
	v_and_b32_e32 v39, 0xffff0000, v16
	v_pk_mul_f32 v[38:39], v[4:5], v[38:39] op_sel_hi:[0,1]
	v_pk_mul_f32 v[34:35], v[38:39], v[34:35]
	v_add_f32_e32 v0, 1.0, v0
	v_rcp_f32_e32 v47, v0
	v_cvt_pk_bf16_f32 v31, v32, v33
	v_pk_mul_f32 v[38:39], v[46:47], v[40:41]
	v_lshlrev_b32_e32 v40, 16, v29
	v_mul_f32_e32 v0, 0xbfb8aa3b, v40
	v_exp_f32_e32 v0, v0
	v_and_b32_e32 v41, 0xffff0000, v29
	v_pk_mul_f32 v[34:35], v[38:39], v[34:35]
	v_lshlrev_b32_e32 v38, 16, v17
	v_add_f32_e32 v0, 1.0, v0
	v_rcp_f32_e32 v46, v0
	v_mul_f32_e32 v0, 0xbfb8aa3b, v41
	v_exp_f32_e32 v0, v0
	v_and_b32_e32 v39, 0xffff0000, v17
	v_pk_mul_f32 v[38:39], v[4:5], v[38:39] op_sel_hi:[0,1]
	v_pk_mul_f32 v[36:37], v[38:39], v[36:37]
	v_add_f32_e32 v0, 1.0, v0
	v_rcp_f32_e32 v47, v0
	v_cvt_pk_bf16_f32 v32, v34, v35
	v_pk_mul_f32 v[38:39], v[46:47], v[40:41]
	s_nop 0
	v_pk_mul_f32 v[36:37], v[38:39], v[36:37]
	v_ashrrev_i32_e32 v38, 7, v53
	v_ashrrev_i32_e32 v39, 31, v38
	v_lshlrev_b64 v[34:35], 11, v[38:39]
	v_cvt_pk_bf16_f32 v33, v36, v37
	v_lshl_add_u64 v[34:35], v[42:43], 0, v[34:35]
	global_store_dwordx4 v[34:35], v[30:33], off
	s_or_b64 exec, exec, s[10:11]
	s_and_saveexec_b64 s[10:11], s[38:39]
	s_cbranch_execz .LBB0_676
.LBB0_688:
	flat_load_dwordx4 v[30:33], v[44:45] nt
	flat_load_dwordx4 v[34:37], v[44:45] offset:16 nt
	v_lshlrev_b32_e32 v40, 16, v22
	v_and_b32_e32 v41, 0xffff0000, v22
	v_mul_f32_e32 v0, 0xbfb8aa3b, v40
	v_mul_f32_e32 v2, 0xbfb8aa3b, v41
	v_exp_f32_e32 v0, v0
	v_exp_f32_e32 v2, v2
	v_lshlrev_b32_e32 v38, 16, v10
	v_and_b32_e32 v39, 0xffff0000, v10
	v_add_f32_e32 v0, 1.0, v0
	v_add_f32_e32 v2, 1.0, v2
	v_rcp_f32_e32 v44, v0
	v_rcp_f32_e32 v45, v2
	v_mov_b32_e32 v0, v5
	v_pk_mul_f32 v[38:39], v[0:1], v[38:39] op_sel_hi:[0,1]
	s_waitcnt vmcnt(0) lgkmcnt(0)
	v_pk_mul_f32 v[30:31], v[38:39], v[30:31]
	v_pk_mul_f32 v[38:39], v[44:45], v[40:41]
	v_lshlrev_b32_e32 v40, 16, v23
	v_mul_f32_e32 v2, 0xbfb8aa3b, v40
	v_exp_f32_e32 v2, v2
	v_and_b32_e32 v41, 0xffff0000, v23
	v_pk_mul_f32 v[30:31], v[38:39], v[30:31]
	v_lshlrev_b32_e32 v38, 16, v11
	v_add_f32_e32 v2, 1.0, v2
	v_rcp_f32_e32 v44, v2
	v_mul_f32_e32 v2, 0xbfb8aa3b, v41
	v_exp_f32_e32 v2, v2
	v_and_b32_e32 v39, 0xffff0000, v11
	v_pk_mul_f32 v[38:39], v[0:1], v[38:39] op_sel_hi:[0,1]
	v_pk_mul_f32 v[32:33], v[38:39], v[32:33]
	v_add_f32_e32 v2, 1.0, v2
	v_rcp_f32_e32 v45, v2
	v_cvt_pk_bf16_f32 v30, v30, v31
	v_pk_mul_f32 v[38:39], v[44:45], v[40:41]
	v_lshlrev_b32_e32 v40, 16, v24
	v_mul_f32_e32 v2, 0xbfb8aa3b, v40
	v_exp_f32_e32 v2, v2
	v_and_b32_e32 v41, 0xffff0000, v24
	v_pk_mul_f32 v[32:33], v[38:39], v[32:33]
	v_lshlrev_b32_e32 v38, 16, v12
	v_add_f32_e32 v2, 1.0, v2
	v_rcp_f32_e32 v44, v2
	v_mul_f32_e32 v2, 0xbfb8aa3b, v41
	v_exp_f32_e32 v2, v2
	v_and_b32_e32 v39, 0xffff0000, v12
	v_pk_mul_f32 v[38:39], v[0:1], v[38:39] op_sel_hi:[0,1]
	v_pk_mul_f32 v[34:35], v[38:39], v[34:35]
	v_add_f32_e32 v2, 1.0, v2
	v_rcp_f32_e32 v45, v2
	v_cvt_pk_bf16_f32 v31, v32, v33
	v_pk_mul_f32 v[38:39], v[44:45], v[40:41]
	s_nop 0
	v_pk_mul_f32 v[34:35], v[38:39], v[34:35]
	v_lshlrev_b32_e32 v38, 16, v13
	v_and_b32_e32 v39, 0xffff0000, v13
	v_lshlrev_b32_e32 v40, 16, v25
	v_and_b32_e32 v41, 0xffff0000, v25
	v_mul_f32_e32 v2, 0xbfb8aa3b, v40
	v_pk_mul_f32 v[38:39], v[0:1], v[38:39] op_sel_hi:[0,1]
	v_mul_f32_e32 v0, 0xbfb8aa3b, v41
	v_exp_f32_e32 v2, v2
	v_exp_f32_e32 v0, v0
	v_pk_mul_f32 v[36:37], v[38:39], v[36:37]
	v_cvt_pk_bf16_f32 v32, v34, v35
	v_add_f32_e32 v2, 1.0, v2
	v_add_f32_e32 v0, 1.0, v0
	v_rcp_f32_e32 v44, v2
	v_rcp_f32_e32 v45, v0
	s_nop 0
	v_pk_mul_f32 v[38:39], v[44:45], v[40:41]
	s_nop 0
	v_pk_mul_f32 v[36:37], v[38:39], v[36:37]
	v_ashrrev_i32_e32 v38, 7, v52
	v_ashrrev_i32_e32 v39, 31, v38
	v_lshlrev_b64 v[34:35], 11, v[38:39]
	v_cvt_pk_bf16_f32 v33, v36, v37
	v_lshl_add_u64 v[34:35], v[42:43], 0, v[34:35]
	global_store_dwordx4 v[34:35], v[30:33], off
	s_branch .LBB0_676
